# prep phase GDN conv task: the six conv-weight row loads of each item are issued at the top of the iteration together with the activation loads (one round trip instead of four)
# baseline (speedup 1.0000x reference)
.Lxb_done_1:
.LBB0_462:
	s_or_b64 exec, exec, s[4:5]
	v_mov_b32_e32 v50, v174
	s_mov_b64 s[66:67], s[80:81]
	s_load_dwordx2 s[14:15], s[92:93], 0x118
	s_waitcnt lgkmcnt(0)
	s_barrier
	s_mov_b32 s74, 0
	s_add_u32 s68, s66, 0x5d52000
	s_addc_u32 s69, s67, 0
	s_ashr_i32 s77, s74, 31
	s_add_u32 s2, s92, s74
	s_waitcnt vmcnt(0)
	v_mov_b32_e32 v0, 0
	s_mov_b32 s75, s88
	s_mov_b32 s76, s86
	s_addc_u32 s3, s93, s77
	s_load_dwordx2 s[10:11], s[2:3], 0xa0
	s_add_u32 s12, s66, 0xb932000
	s_addc_u32 s13, s67, 0
	s_add_i32 s2, s76, s75
	v_mov_b32_e32 v25, 0
	s_cmpk_gt_i32 s2, 0x8ff
	v_lshlrev_b32_e32 v42, 3, v50
	s_mov_b32 s3, s75
	s_cbranch_scc1 .LBB0_477
	v_and_b32_e32 v26, 0xf8, v42
	s_lshl_b32 s20, s76, 1
	s_lshl_b32 s21, s2, 9
	s_lshl_b32 s22, s76, 10
	s_lshl_b32 s23, s2, 12
	s_lshl_b32 s24, s76, 13
	s_lshl_b32 s25, s75, 9
	s_lshl_b32 s26, s75, 12
	s_mov_b32 s27, 0x2aaaaaab
	s_mov_b32 s28, 0x5ffff
	v_mov_b32_e32 v27, 0xff
	v_mov_b32_e32 v35, 0x7ff
	s_movk_i32 s29, 0x1660
	v_mov_b64_e32 v[28:29], s[68:69]
	s_movk_i32 s30, 0xfd00
	s_mov_b64 s[16:17], 0x840
	s_movk_i32 s31, 0x1000
	s_movk_i32 s33, 0xffa0
	s_mov_b64 s[18:19], 0x1800
	s_mov_b32 s34, 0x800000
	s_mov_b32 s35, 0x600000
	v_mov_b32_e32 v43, 0x3e000000
	v_mov_b32_e32 v44, v42
	v_mov_b32_e32 v45, v50
	s_mov_b32 s3, s75
	s_waitcnt lgkmcnt(0)
	s_branch .LBB0_465

.LBB0_465:
	v_add_u32_e32 v24, s25, v45
	v_mul_hi_i32 v0, v24, s27
	v_lshrrev_b32_e32 v1, 31, v0
	v_ashrrev_i32_e32 v0, 4, v0
	v_add_u32_e32 v32, v0, v1
	v_mul_lo_u32 v2, v32, s30
	v_add3_u32 v38, s26, v44, v2
	v_mad_i64_i32 v[0:1], s[4:5], v32, s29, v[28:29]
	v_ashrrev_i32_e32 v39, 31, v38
	v_lshl_add_u64 v[240:241], v[38:39], 2, s[10:11]
	v_lshl_add_u64 v[242:243], v[240:241], 0, s[18:19]
	global_load_dwordx4 v[176:179], v[240:241], off
	global_load_dwordx4 v[180:183], v[240:241], off offset:16
	global_load_dwordx4 v[184:187], v[240:241], off offset:3072
	global_load_dwordx4 v[188:191], v[240:241], off offset:3088
	global_load_dwordx4 v[192:195], v[242:243], off
	global_load_dwordx4 v[196:199], v[242:243], off offset:16
	v_lshl_add_u64 v[0:1], v[38:39], 1, v[0:1]
	flat_load_dwordx4 v[16:19], v[0:1] offset:2112
	v_cmp_lt_i32_e32 vcc, s28, v24
	v_lshl_add_u64 v[0:1], v[0:1], 0, s[16:17]
	v_mov_b32_e32 v14, 0
	v_cndmask_b32_e32 v2, v27, v35, vcc
	v_and_b32_e32 v3, v2, v32
	v_cmp_ne_u32_e32 vcc, 0, v3
	v_mov_b32_e32 v22, 0
	v_mov_b32_e32 v23, 0
	v_mov_b32_e32 v20, 0
	v_mov_b32_e32 v21, 0
	s_and_saveexec_b64 s[4:5], vcc
	s_cbranch_execz .LBB0_467
	v_add_co_u32_e32 v4, vcc, 0xffffe9a0, v0
	s_nop 1
	v_addc_co_u32_e32 v5, vcc, -1, v1, vcc
	flat_load_dwordx4 v[20:23], v[4:5]

.LBB0_469:
	s_or_b64 exec, exec, s[4:5]
	v_add_u32_e32 v34, s21, v45
	v_mul_hi_i32 v0, v34, s27
	v_lshrrev_b32_e32 v1, 31, v0
	v_ashrrev_i32_e32 v0, 4, v0
	v_add_u32_e32 v30, v0, v1
	v_mul_lo_u32 v2, v30, s30
	v_add3_u32 v36, s23, v44, v2
	v_mad_i64_i32 v[0:1], s[4:5], v30, s29, v[28:29]
	v_ashrrev_i32_e32 v37, 31, v36
	v_lshl_add_u64 v[244:245], v[36:37], 2, s[10:11]
	v_lshl_add_u64 v[246:247], v[244:245], 0, s[18:19]
	global_load_dwordx4 v[200:203], v[244:245], off
	global_load_dwordx4 v[204:207], v[244:245], off offset:16
	global_load_dwordx4 v[208:211], v[244:245], off offset:3072
	global_load_dwordx4 v[212:215], v[244:245], off offset:3088
	global_load_dwordx4 v[216:219], v[246:247], off
	global_load_dwordx4 v[220:223], v[246:247], off offset:16
	v_lshl_add_u64 v[2:3], v[36:37], 1, v[0:1]
	flat_load_dwordx4 v[4:7], v[2:3] offset:2112
	v_cmp_lt_i32_e32 vcc, s28, v34
	v_lshl_add_u64 v[40:41], v[2:3], 0, s[16:17]
	v_mov_b32_e32 v2, 0
	v_cndmask_b32_e32 v0, v27, v35, vcc
	v_and_b32_e32 v1, v0, v30
	v_cmp_ne_u32_e32 vcc, 0, v1
	v_mov_b32_e32 v10, 0
	v_mov_b32_e32 v11, 0
	v_mov_b32_e32 v8, 0
	v_mov_b32_e32 v9, 0
	s_and_saveexec_b64 s[4:5], vcc
	s_cbranch_execz .LBB0_471
	v_add_co_u32_e32 v8, vcc, 0xffffe9a0, v40
	s_nop 1
	v_addc_co_u32_e32 v9, vcc, -1, v41, vcc
	flat_load_dwordx4 v[8:11], v[8:9]

.LBB0_473:
	s_or_b64 exec, exec, s[4:5]
	s_waitcnt lgkmcnt(0)
	v_lshl_add_u64 v[40:41], v[38:39], 2, s[10:11]
	s_waitcnt vmcnt(0) lgkmcnt(0)
	s_nop 0
	s_nop 0
	v_add_co_u32_e32 v38, vcc, s31, v40
	s_nop 0
	v_lshlrev_b32_e32 v68, 16, v20
	v_addc_co_u32_e32 v39, vcc, 0, v41, vcc
	s_nop 0
	s_nop 0
	s_nop 0
	v_and_b32_e32 v69, 0xffff0000, v20
	v_lshlrev_b32_e32 v70, 16, v21
	v_and_b32_e32 v71, 0xffff0000, v21
	v_lshl_add_u64 v[20:21], v[40:41], 0, s[18:19]
	v_mad_u64_u32 v[38:39], s[4:5], v32, s33, v[24:25]
	v_lshlrev_b32_e32 v72, 16, v22
	v_and_b32_e32 v73, 0xffff0000, v22
	v_lshlrev_b32_e32 v24, 16, v23
	v_and_b32_e32 v74, 0xffff0000, v23
	s_nop 0
	v_lshlrev_b32_e32 v76, 16, v16
	v_and_b32_e32 v77, 0xffff0000, v16
	v_lshlrev_b32_e32 v16, 16, v17
	v_and_b32_e32 v17, 0xffff0000, v17
	v_lshlrev_b32_e32 v40, 16, v12
	v_and_b32_e32 v41, 0xffff0000, v12
	v_lshlrev_b32_e32 v12, 16, v13
	v_and_b32_e32 v13, 0xffff0000, v13
	v_and_b32_e32 v75, 0xffff0000, v15
	v_lshlrev_b32_e32 v80, 16, v14
	v_and_b32_e32 v81, 0xffff0000, v14
	v_lshlrev_b32_e32 v78, 16, v18
	v_and_b32_e32 v79, 0xffff0000, v18
	v_lshlrev_b32_e32 v18, 16, v19
	v_and_b32_e32 v19, 0xffff0000, v19
	v_pk_mul_f32 v[52:53], v[184:185], v[76:77]
	v_pk_mul_f32 v[16:17], v[186:187], v[16:17]
	v_pk_fma_f32 v[46:47], v[176:177], v[68:69], v[52:53]
	v_pk_fma_f32 v[16:17], v[178:179], v[70:71], v[16:17]
	s_nop 0
	v_pk_fma_f32 v[40:41], v[192:193], v[40:41], v[46:47]
	v_pk_fma_f32 v[16:17], v[194:195], v[12:13], v[16:17]
	v_mul_f32_e32 v12, 0xbfb8aa3b, v40
	v_mul_f32_e32 v13, 0xbfb8aa3b, v41
	v_exp_f32_e32 v12, v12
	v_exp_f32_e32 v13, v13
	v_mul_f32_e32 v31, 0xbfb8aa3b, v16
	v_mul_f32_e32 v33, 0xbfb8aa3b, v17
	v_exp_f32_e32 v46, v31
	v_exp_f32_e32 v47, v33
	v_pk_add_f32 v[12:13], v[12:13], 1.0 op_sel_hi:[1,0]
	v_lshlrev_b32_e32 v31, 16, v15
	v_div_scale_f32 v33, s[4:5], v13, v13, v41
	v_pk_add_f32 v[14:15], v[46:47], 1.0 op_sel_hi:[1,0]
	v_div_scale_f32 v46, s[4:5], v12, v12, v40
	v_rcp_f32_e32 v53, v33
	v_div_scale_f32 v48, s[6:7], v15, v15, v17
	v_rcp_f32_e32 v54, v46
	v_rcp_f32_e32 v55, v48
	v_fma_f32 v57, -v33, v53, 1.0
	v_div_scale_f32 v39, vcc, v41, v13, v41
	v_fma_f32 v58, -v46, v54, 1.0
	v_fmac_f32_e32 v53, v57, v53
	v_div_scale_f32 v47, s[4:5], v40, v12, v40
	v_fma_f32 v59, -v48, v55, 1.0
	v_fmac_f32_e32 v54, v58, v54
	v_mul_f32_e32 v57, v39, v53
	v_div_scale_f32 v49, s[6:7], v17, v15, v17
	v_fmac_f32_e32 v55, v59, v55
	v_mul_f32_e32 v58, v47, v54
	v_fma_f32 v69, -v33, v57, v39
	v_mul_f32_e32 v59, v49, v55
	v_fma_f32 v70, -v46, v58, v47
	v_fmac_f32_e32 v57, v69, v53
	v_fma_f32 v71, -v48, v59, v49
	v_fmac_f32_e32 v58, v70, v54
	v_fma_f32 v33, -v33, v57, v39
	v_fmac_f32_e32 v59, v71, v55
	v_fma_f32 v39, -v46, v58, v47
	v_div_fmas_f32 v33, v33, v53, v57
	s_mov_b64 vcc, s[4:5]
	v_fma_f32 v46, -v48, v59, v49
	v_div_fixup_f32 v13, v33, v13, v41
	v_div_fmas_f32 v33, v39, v54, v58
	s_mov_b64 vcc, s[6:7]
	v_div_fixup_f32 v12, v33, v12, v40
	v_div_fmas_f32 v33, v46, v55, v59
	s_nop 0
	v_pk_mul_f32 v[46:47], v[188:189], v[78:79]
	v_div_scale_f32 v51, s[8:9], v14, v14, v16
	v_pk_fma_f32 v[46:47], v[180:181], v[72:73], v[46:47]
	v_div_fixup_f32 v15, v33, v15, v17
	s_nop 0
	v_pk_fma_f32 v[20:21], v[196:197], v[80:81], v[46:47]
	v_rcp_f32_e32 v56, v51
	v_mul_f32_e32 v17, 0xbfb8aa3b, v20
	v_exp_f32_e32 v46, v17
	v_mul_f32_e32 v17, 0xbfb8aa3b, v21
	v_exp_f32_e32 v47, v17
	v_fma_f32 v68, -v51, v56, 1.0
	v_div_scale_f32 v52, s[8:9], v16, v14, v16
	v_fmac_f32_e32 v56, v68, v56
	v_pk_add_f32 v[46:47], v[46:47], 1.0 op_sel_hi:[1,0]
	v_mul_f32_e32 v68, v52, v56
	v_div_scale_f32 v33, s[4:5], v47, v47, v21
	v_fma_f32 v17, -v51, v68, v52
	v_rcp_f32_e32 v39, v33
	v_fmac_f32_e32 v68, v17, v56
	v_fma_f32 v17, -v51, v68, v52
	s_mov_b64 vcc, s[8:9]
	v_div_fmas_f32 v17, v17, v56, v68
	v_div_fixup_f32 v14, v17, v14, v16
	v_fma_f32 v16, -v33, v39, 1.0
	v_fmac_f32_e32 v39, v16, v39
	v_div_scale_f32 v16, vcc, v21, v47, v21
	v_mul_f32_e32 v17, v16, v39
	v_fma_f32 v51, -v33, v17, v16
	v_mul_f32_e32 v54, v198, v31
	v_mov_b32_e32 v22, v183
	v_fmac_f32_e32 v17, v51, v39
	v_mov_b32_e32 v23, v199
	v_pk_mul_f32 v[22:23], v[22:23], v[74:75]
	v_fma_f32 v16, -v33, v17, v16
	v_div_scale_f32 v33, s[4:5], v46, v46, v20
	v_mul_f32_e32 v52, v182, v24
	v_mov_b32_e32 v53, v22
	v_rcp_f32_e32 v51, v33
	v_pk_fma_f32 v[18:19], v[190:191], v[18:19], v[52:53]
	v_mov_b32_e32 v55, v23
	v_pk_add_f32 v[18:19], v[18:19], v[54:55]
	v_div_fmas_f32 v16, v16, v39, v17
	v_mul_f32_e32 v22, 0xbfb8aa3b, v18
	v_mul_f32_e32 v23, 0xbfb8aa3b, v19
	v_exp_f32_e32 v22, v22
	v_exp_f32_e32 v23, v23
	v_div_fixup_f32 v17, v16, v47, v21
	v_fma_f32 v16, -v33, v51, 1.0
	v_fmac_f32_e32 v51, v16, v51
	v_div_scale_f32 v16, vcc, v20, v46, v20
	v_mul_f32_e32 v21, v16, v51
	v_fma_f32 v24, -v33, v21, v16
	v_pk_add_f32 v[22:23], v[22:23], 1.0 op_sel_hi:[1,0]
	v_fmac_f32_e32 v21, v24, v51
	v_div_scale_f32 v24, s[4:5], v23, v23, v19
	v_rcp_f32_e32 v31, v24
	v_fma_f32 v16, -v33, v21, v16
	v_div_fmas_f32 v16, v16, v51, v21
	v_div_fixup_f32 v16, v16, v46, v20
	v_fma_f32 v33, -v24, v31, 1.0
	v_fmac_f32_e32 v31, v33, v31
	v_div_scale_f32 v33, vcc, v19, v23, v19
	v_mul_f32_e32 v39, v33, v31
	v_fma_f32 v46, -v24, v39, v33
	v_fmac_f32_e32 v39, v46, v31
	v_fma_f32 v24, -v24, v39, v33
	v_div_scale_f32 v33, s[4:5], v22, v22, v18
	v_rcp_f32_e32 v46, v33
	v_div_fmas_f32 v24, v24, v31, v39
	v_div_fixup_f32 v19, v24, v23, v19
	v_pk_mul_f32 v[40:41], v[12:13], v[12:13]
	v_fma_f32 v23, -v33, v46, 1.0
	v_fmac_f32_e32 v46, v23, v46
	v_div_scale_f32 v23, vcc, v18, v22, v18
	v_mul_f32_e32 v24, v23, v46
	v_fma_f32 v31, -v33, v24, v23
	v_fmac_f32_e32 v24, v31, v46
	v_fma_f32 v23, -v33, v24, v23
	v_pk_mul_f32 v[48:49], v[14:15], v[14:15]
	v_div_fmas_f32 v23, v23, v46, v24
	v_add_f32_e32 v24, v40, v41
	v_add_f32_e32 v24, v24, v48
	v_pk_mul_f32 v[20:21], v[16:17], v[16:17]
	v_add_f32_e32 v24, v24, v49
	v_div_fixup_f32 v18, v23, v22, v18
	v_add_f32_e32 v20, v24, v20
	v_pk_mul_f32 v[22:23], v[18:19], v[18:19]
	v_add_f32_e32 v20, v20, v21
	v_add_f32_e32 v20, v20, v22
	v_add_f32_e32 v20, v20, v23
	v_cmp_gt_i32_e32 vcc, 64, v38
	s_nop 0
	v_add_f32_dpp v20, v20, v20 quad_perm:[1,0,3,2] row_mask:0xf bank_mask:0xf bound_ctrl:1
	s_nop 1
	v_add_f32_dpp v20, v20, v20 quad_perm:[2,3,0,1] row_mask:0xf bank_mask:0xf bound_ctrl:1
	s_nop 1
	v_mov_b32_dpp v21, v20 row_half_mirror row_mask:0xf bank_mask:0xf bound_ctrl:1
	s_and_saveexec_b64 s[6:7], vcc
	s_cbranch_execz .LBB0_475
	v_add_f32_e32 v20, v20, v21
	v_add_f32_e32 v20, 0x358637bd, v20
	v_mul_f32_e32 v21, 0x4b800000, v20
	v_cmp_gt_f32_e32 vcc, s34, v20
	v_cmp_gt_i32_e64 s[4:5], 32, v38
	s_nop 0
	v_cndmask_b32_e32 v20, v20, v21, vcc
	v_rsq_f32_e32 v20, v20
	v_cndmask_b32_e64 v21, 1.0, v43, s[4:5]
	v_mul_f32_e32 v22, 0x45800000, v20
	v_cndmask_b32_e32 v20, v20, v22, vcc
	v_mul_f32_e32 v20, v21, v20
	v_pk_mul_f32 v[18:19], v[18:19], v[20:21] op_sel_hi:[1,0]
	v_pk_mul_f32 v[16:17], v[16:17], v[20:21] op_sel_hi:[1,0]
	v_pk_mul_f32 v[14:15], v[14:15], v[20:21] op_sel_hi:[1,0]
	v_pk_mul_f32 v[12:13], v[12:13], v[20:21] op_sel_hi:[1,0]
.LBB0_475:
	s_or_b64 exec, exec, s[6:7]
	v_ashrrev_i32_e32 v33, 31, v32
	v_ashrrev_i32_e32 v22, 5, v38
	v_mov_b64_e32 v[20:21], s[12:13]
	v_mad_i64_i32 v[20:21], s[4:5], v22, s35, v[20:21]
	v_lshlrev_b64 v[22:23], 9, v[32:33]
	v_lshl_add_u64 v[20:21], v[20:21], 0, v[22:23]
	v_lshlrev_b32_e32 v24, 1, v26
	v_lshl_add_u64 v[20:21], v[20:21], 0, v[24:25]
	v_cvt_pk_bf16_f32 v12, v12, v13
	v_cvt_pk_bf16_f32 v13, v14, v15
	v_cvt_pk_bf16_f32 v14, v16, v17
	v_cvt_pk_bf16_f32 v15, v18, v19
	flat_store_dwordx4 v[20:21], v[12:15]
	v_lshl_add_u64 v[22:23], v[36:37], 2, s[10:11]
	s_nop 0
	s_nop 0
	v_add_co_u32_e32 v12, vcc, s31, v22
	v_lshlrev_b32_e32 v32, 16, v8
	s_nop 0
	v_addc_co_u32_e32 v13, vcc, 0, v23, vcc
	s_nop 0
	s_nop 0
	s_nop 0
	v_mad_u64_u32 v[12:13], s[4:5], v30, s33, v[34:35]
	v_and_b32_e32 v33, 0xffff0000, v8
	v_lshlrev_b32_e32 v40, 16, v9
	v_and_b32_e32 v41, 0xffff0000, v9
	v_lshl_add_u64 v[8:9], v[22:23], 0, s[18:19]
	v_lshlrev_b32_e32 v56, 16, v10
	v_and_b32_e32 v57, 0xffff0000, v10
	v_lshlrev_b32_e32 v13, 16, v11
	v_and_b32_e32 v58, 0xffff0000, v11
	s_nop 0
	v_lshlrev_b32_e32 v60, 16, v4
	v_and_b32_e32 v61, 0xffff0000, v4
	v_lshlrev_b32_e32 v4, 16, v5
	v_and_b32_e32 v5, 0xffff0000, v5
	v_lshlrev_b32_e32 v22, 16, v0
	v_and_b32_e32 v23, 0xffff0000, v0
	v_lshlrev_b32_e32 v0, 16, v1
	v_and_b32_e32 v1, 0xffff0000, v1
	v_and_b32_e32 v59, 0xffff0000, v3
	v_lshlrev_b32_e32 v64, 16, v2
	v_and_b32_e32 v65, 0xffff0000, v2
	v_lshlrev_b32_e32 v62, 16, v6
	v_and_b32_e32 v63, 0xffff0000, v6
	v_lshlrev_b32_e32 v6, 16, v7
	v_and_b32_e32 v7, 0xffff0000, v7
	s_nop 0
	v_pk_mul_f32 v[18:19], v[208:209], v[60:61]
	v_pk_mul_f32 v[4:5], v[210:211], v[4:5]
	v_pk_fma_f32 v[14:15], v[200:201], v[32:33], v[18:19]
	v_pk_fma_f32 v[4:5], v[202:203], v[40:41], v[4:5]
	v_pk_fma_f32 v[14:15], v[216:217], v[22:23], v[14:15]
	v_pk_fma_f32 v[4:5], v[218:219], v[0:1], v[4:5]
	v_mul_f32_e32 v0, 0xbfb8aa3b, v14
	v_mul_f32_e32 v1, 0xbfb8aa3b, v15
	v_mul_f32_e32 v16, 0xbfb8aa3b, v4
	v_mul_f32_e32 v17, 0xbfb8aa3b, v5
	v_exp_f32_e32 v0, v0
	v_exp_f32_e32 v1, v1
	v_exp_f32_e32 v16, v16
	v_exp_f32_e32 v17, v17
	v_lshlrev_b32_e32 v21, 16, v3
	v_pk_add_f32 v[0:1], v[0:1], 1.0 op_sel_hi:[1,0]
	v_pk_add_f32 v[2:3], v[16:17], 1.0 op_sel_hi:[1,0]
	v_div_scale_f32 v16, s[4:5], v1, v1, v15
	v_div_scale_f32 v18, s[4:5], v0, v0, v14
	v_rcp_f32_e32 v22, v16
	v_div_scale_f32 v20, s[6:7], v3, v3, v5
	v_rcp_f32_e32 v23, v18
	v_rcp_f32_e32 v31, v20
	v_fma_f32 v33, -v16, v22, 1.0
	v_div_scale_f32 v17, vcc, v15, v1, v15
	v_fma_f32 v34, -v18, v23, 1.0
	v_fmac_f32_e32 v22, v33, v22
	v_div_scale_f32 v19, s[4:5], v14, v0, v14
	v_fma_f32 v36, -v20, v31, 1.0
	v_fmac_f32_e32 v23, v34, v23
	v_mul_f32_e32 v33, v17, v22
	v_div_scale_f32 v32, s[6:7], v5, v3, v5
	v_fmac_f32_e32 v31, v36, v31
	v_mul_f32_e32 v34, v19, v23
	v_fma_f32 v37, -v16, v33, v17
	v_mul_f32_e32 v36, v32, v31
	v_fma_f32 v38, -v18, v34, v19
	v_fmac_f32_e32 v33, v37, v22
	v_fma_f32 v39, -v20, v36, v32
	v_fmac_f32_e32 v34, v38, v23
	v_fma_f32 v16, -v16, v33, v17
	v_fmac_f32_e32 v36, v39, v31
	v_fma_f32 v17, -v18, v34, v19
	v_div_fmas_f32 v16, v16, v22, v33
	s_mov_b64 vcc, s[4:5]
	v_fma_f32 v18, -v20, v36, v32
	v_div_fixup_f32 v1, v16, v1, v15
	v_div_fmas_f32 v15, v17, v23, v34
	s_mov_b64 vcc, s[6:7]
	v_div_fmas_f32 v16, v18, v31, v36
	v_div_scale_f32 v19, s[4:5], v2, v2, v4
	v_div_fixup_f32 v3, v16, v3, v5
	v_pk_mul_f32 v[16:17], v[212:213], v[62:63]
	v_rcp_f32_e32 v20, v19
	v_pk_fma_f32 v[16:17], v[204:205], v[56:57], v[16:17]
	v_div_fixup_f32 v0, v15, v0, v14
	v_pk_fma_f32 v[8:9], v[220:221], v[64:65], v[16:17]
	v_fma_f32 v5, -v19, v20, 1.0
	v_mul_f32_e32 v16, 0xbfb8aa3b, v8
	v_mul_f32_e32 v17, 0xbfb8aa3b, v9
	v_exp_f32_e32 v16, v16
	v_exp_f32_e32 v17, v17
	v_fmac_f32_e32 v20, v5, v20
	v_div_scale_f32 v5, vcc, v4, v2, v4
	v_mul_f32_e32 v18, v5, v20
	v_fma_f32 v22, -v19, v18, v5
	v_pk_add_f32 v[16:17], v[16:17], 1.0 op_sel_hi:[1,0]
	v_fmac_f32_e32 v18, v22, v20
	v_div_scale_f32 v22, s[4:5], v17, v17, v9
	v_rcp_f32_e32 v23, v22
	v_fma_f32 v5, -v19, v18, v5
	v_div_fmas_f32 v5, v5, v20, v18
	v_div_fixup_f32 v2, v5, v2, v4
	v_fma_f32 v4, -v22, v23, 1.0
	v_fmac_f32_e32 v23, v4, v23
	v_div_scale_f32 v4, vcc, v9, v17, v9
	v_mul_f32_e32 v5, v4, v23
	v_fma_f32 v20, -v22, v5, v4
	v_fmac_f32_e32 v5, v20, v23
	v_fma_f32 v4, -v22, v5, v4
	v_mul_f32_e32 v22, v222, v21
	v_mov_b32_e32 v10, v207
	v_mov_b32_e32 v11, v223
	v_pk_mul_f32 v[10:11], v[10:11], v[58:59]
	v_div_scale_f32 v31, s[4:5], v16, v16, v8
	v_mul_f32_e32 v20, v206, v13
	v_mov_b32_e32 v21, v10
	v_rcp_f32_e32 v32, v31
	v_div_fmas_f32 v4, v4, v23, v5
	v_pk_fma_f32 v[6:7], v[214:215], v[6:7], v[20:21]
	v_mov_b32_e32 v23, v11
	v_pk_add_f32 v[6:7], v[6:7], v[22:23]
	v_div_fixup_f32 v5, v4, v17, v9
	v_mul_f32_e32 v10, 0xbfb8aa3b, v6
	v_mul_f32_e32 v11, 0xbfb8aa3b, v7
	v_exp_f32_e32 v10, v10
	v_exp_f32_e32 v11, v11
	v_fma_f32 v4, -v31, v32, 1.0
	v_fmac_f32_e32 v32, v4, v32
	v_div_scale_f32 v4, vcc, v8, v16, v8
	v_mul_f32_e32 v9, v4, v32
	v_fma_f32 v13, -v31, v9, v4
	v_pk_add_f32 v[10:11], v[10:11], 1.0 op_sel_hi:[1,0]
	v_fmac_f32_e32 v9, v13, v32
	v_div_scale_f32 v13, s[4:5], v11, v11, v7
	v_rcp_f32_e32 v17, v13
	v_fma_f32 v4, -v31, v9, v4
	v_div_fmas_f32 v4, v4, v32, v9
	v_div_fixup_f32 v4, v4, v16, v8
	v_fma_f32 v16, -v13, v17, 1.0
	v_fmac_f32_e32 v17, v16, v17
	v_div_scale_f32 v16, vcc, v7, v11, v7
	v_mul_f32_e32 v20, v16, v17
	v_fma_f32 v21, -v13, v20, v16
	v_fmac_f32_e32 v20, v21, v17
	v_fma_f32 v13, -v13, v20, v16
	v_div_scale_f32 v16, s[4:5], v10, v10, v6
	v_rcp_f32_e32 v21, v16
	v_div_fmas_f32 v13, v13, v17, v20
	v_div_fixup_f32 v7, v13, v11, v7
	v_pk_mul_f32 v[14:15], v[0:1], v[0:1]
	v_fma_f32 v11, -v16, v21, 1.0
	v_fmac_f32_e32 v21, v11, v21
	v_div_scale_f32 v11, vcc, v6, v10, v6
	v_mul_f32_e32 v13, v11, v21
	v_fma_f32 v17, -v16, v13, v11
	v_fmac_f32_e32 v13, v17, v21
	v_fma_f32 v11, -v16, v13, v11
	v_pk_mul_f32 v[18:19], v[2:3], v[2:3]
	v_div_fmas_f32 v11, v11, v21, v13
	v_add_f32_e32 v13, v14, v15
	v_add_f32_e32 v13, v13, v18
	v_pk_mul_f32 v[8:9], v[4:5], v[4:5]
	v_add_f32_e32 v13, v13, v19
	v_div_fixup_f32 v6, v11, v10, v6
	v_add_f32_e32 v8, v13, v8
	v_pk_mul_f32 v[10:11], v[6:7], v[6:7]
	v_add_f32_e32 v8, v8, v9
	v_add_f32_e32 v8, v8, v10
	v_add_f32_e32 v8, v8, v11
	v_cmp_gt_i32_e32 vcc, 64, v12
	s_nop 0
	v_add_f32_dpp v8, v8, v8 quad_perm:[1,0,3,2] row_mask:0xf bank_mask:0xf bound_ctrl:1
	s_nop 1
	v_add_f32_dpp v8, v8, v8 quad_perm:[2,3,0,1] row_mask:0xf bank_mask:0xf bound_ctrl:1
	s_nop 1
	v_mov_b32_dpp v9, v8 row_half_mirror row_mask:0xf bank_mask:0xf bound_ctrl:1
	s_and_saveexec_b64 s[6:7], vcc
	s_cbranch_execz .LBB0_464
	v_add_f32_e32 v8, v8, v9
	v_add_f32_e32 v8, 0x358637bd, v8
	v_mul_f32_e32 v9, 0x4b800000, v8
	v_cmp_gt_f32_e32 vcc, s34, v8
	v_cmp_gt_i32_e64 s[4:5], 32, v12
	s_nop 0
	v_cndmask_b32_e32 v8, v8, v9, vcc
	v_rsq_f32_e32 v8, v8
	v_cndmask_b32_e64 v9, 1.0, v43, s[4:5]
	v_mul_f32_e32 v10, 0x45800000, v8
	v_cndmask_b32_e32 v8, v8, v10, vcc
	v_mul_f32_e32 v8, v9, v8
	v_pk_mul_f32 v[6:7], v[6:7], v[8:9] op_sel_hi:[1,0]
	v_pk_mul_f32 v[4:5], v[4:5], v[8:9] op_sel_hi:[1,0]
	v_pk_mul_f32 v[2:3], v[2:3], v[8:9] op_sel_hi:[1,0]
	v_pk_mul_f32 v[0:1], v[0:1], v[8:9] op_sel_hi:[1,0]
	s_branch .LBB0_464
.LBB0_477:
	s_cmpk_gt_i32 s3, 0x8ff
	s_cbranch_scc1 .LBB0_486
	v_and_b32_e32 v0, 0xf8, v42
	v_mov_b32_e32 v13, 0
	v_lshl_add_u32 v14, s3, 9, v50
	s_lshl_b32 s20, s76, 9
	v_lshl_add_u32 v16, s3, 12, v42
	s_lshl_b32 s21, s76, 12
	s_mov_b32 s22, 0x2aaaaaab
	s_mov_b32 s23, 0x5ffff
	v_mov_b32_e32 v15, 0xff
	v_mov_b32_e32 v17, 0x7ff
	s_movk_i32 s24, 0x1660
	v_mov_b64_e32 v[18:19], s[68:69]
	s_movk_i32 s25, 0xfd00
	s_mov_b64 s[16:17], 0x840
	s_movk_i32 s26, 0x1000
	s_movk_i32 s27, 0xffa0
	s_mov_b64 s[18:19], 0x1800
	s_mov_b32 s28, 0x800000
	s_mov_b32 s29, 0x600000
	v_mov_b64_e32 v[20:21], s[12:13]
	v_lshlrev_b32_e32 v12, 1, v0
	v_mov_b32_e32 v28, 0x3e000000
	s_waitcnt lgkmcnt(0)
	s_branch .LBB0_480

.LBB0_480:
	s_nop 0
	v_mul_hi_i32 v0, v14, s22
	v_lshrrev_b32_e32 v1, 31, v0
	v_ashrrev_i32_e32 v0, 4, v0
	v_add_u32_e32 v22, v0, v1
	v_mad_u64_u32 v[24:25], s[4:5], v22, s25, v[16:17]
	v_mad_i64_i32 v[0:1], s[4:5], v22, s24, v[18:19]
	v_ashrrev_i32_e32 v25, 31, v24
	v_lshl_add_u64 v[240:241], v[24:25], 2, s[10:11]
	v_lshl_add_u64 v[242:243], v[240:241], 0, s[18:19]
	global_load_dwordx4 v[176:179], v[240:241], off
	global_load_dwordx4 v[180:183], v[240:241], off offset:16
	global_load_dwordx4 v[184:187], v[240:241], off offset:3072
	global_load_dwordx4 v[188:191], v[240:241], off offset:3088
	global_load_dwordx4 v[192:195], v[242:243], off
	global_load_dwordx4 v[196:199], v[242:243], off offset:16
	v_lshl_add_u64 v[2:3], v[24:25], 1, v[0:1]
	flat_load_dwordx4 v[4:7], v[2:3] offset:2112
	v_cmp_lt_i32_e32 vcc, s23, v14
	v_lshl_add_u64 v[26:27], v[2:3], 0, s[16:17]
	v_mov_b32_e32 v10, 0
	v_cndmask_b32_e32 v0, v15, v17, vcc
	v_and_b32_e32 v1, v0, v22
	v_cmp_ne_u32_e32 vcc, 0, v1
	v_mov_b32_e32 v11, 0
	v_mov_b32_e32 v8, 0
	v_mov_b32_e32 v9, 0
	s_and_saveexec_b64 s[4:5], vcc
	s_cbranch_execz .LBB0_482
	v_add_co_u32_e32 v2, vcc, 0xffffe9a0, v26
	s_nop 1
	v_addc_co_u32_e32 v3, vcc, -1, v27, vcc
	flat_load_dwordx4 v[8:11], v[2:3]

.LBB0_484:
	s_or_b64 exec, exec, s[4:5]
	s_waitcnt lgkmcnt(0)
	v_lshl_add_u64 v[26:27], v[24:25], 2, s[10:11]
	s_waitcnt vmcnt(0) lgkmcnt(0)
	s_nop 0
	s_nop 0
	v_add_co_u32_e32 v24, vcc, s26, v26
	s_nop 0
	v_lshlrev_b32_e32 v48, 16, v8
	v_addc_co_u32_e32 v25, vcc, 0, v27, vcc
	s_nop 0
	s_nop 0
	s_nop 0
	v_and_b32_e32 v49, 0xffff0000, v8
	v_lshlrev_b32_e32 v56, 16, v9
	v_and_b32_e32 v57, 0xffff0000, v9
	v_lshl_add_u64 v[8:9], v[26:27], 0, s[18:19]
	v_lshlrev_b32_e32 v58, 16, v10
	v_and_b32_e32 v59, 0xffff0000, v10
	v_lshlrev_b32_e32 v23, 16, v11
	v_and_b32_e32 v60, 0xffff0000, v11
	s_nop 0
	v_lshlrev_b32_e32 v62, 16, v4
	v_and_b32_e32 v63, 0xffff0000, v4
	v_lshlrev_b32_e32 v4, 16, v5
	v_and_b32_e32 v5, 0xffff0000, v5
	v_lshlrev_b32_e32 v26, 16, v0
	v_and_b32_e32 v27, 0xffff0000, v0
	v_lshlrev_b32_e32 v0, 16, v1
	v_and_b32_e32 v1, 0xffff0000, v1
	v_mad_u64_u32 v[24:25], s[4:5], v22, s27, v[14:15]
	v_and_b32_e32 v61, 0xffff0000, v3
	v_lshlrev_b32_e32 v66, 16, v2
	v_and_b32_e32 v67, 0xffff0000, v2
	v_lshlrev_b32_e32 v64, 16, v6
	v_and_b32_e32 v65, 0xffff0000, v6
	v_lshlrev_b32_e32 v6, 16, v7
	v_and_b32_e32 v7, 0xffff0000, v7
	v_pk_mul_f32 v[34:35], v[184:185], v[62:63]
	v_pk_mul_f32 v[4:5], v[186:187], v[4:5]
	v_pk_fma_f32 v[30:31], v[176:177], v[48:49], v[34:35]
	v_pk_fma_f32 v[4:5], v[178:179], v[56:57], v[4:5]
	s_nop 0
	v_pk_fma_f32 v[26:27], v[192:193], v[26:27], v[30:31]
	v_pk_fma_f32 v[4:5], v[194:195], v[0:1], v[4:5]
	v_mul_f32_e32 v0, 0xbfb8aa3b, v26
	v_mul_f32_e32 v1, 0xbfb8aa3b, v27
	v_exp_f32_e32 v0, v0
	v_exp_f32_e32 v1, v1
	v_mul_f32_e32 v25, 0xbfb8aa3b, v4
	v_mul_f32_e32 v29, 0xbfb8aa3b, v5
	v_exp_f32_e32 v30, v25
	v_exp_f32_e32 v31, v29
	v_pk_add_f32 v[0:1], v[0:1], 1.0 op_sel_hi:[1,0]
	v_lshlrev_b32_e32 v25, 16, v3
	v_div_scale_f32 v29, s[4:5], v1, v1, v27
	v_pk_add_f32 v[2:3], v[30:31], 1.0 op_sel_hi:[1,0]
	v_div_scale_f32 v31, s[4:5], v0, v0, v26
	v_rcp_f32_e32 v37, v29
	v_div_scale_f32 v33, s[6:7], v3, v3, v5
	v_rcp_f32_e32 v38, v31
	v_rcp_f32_e32 v39, v33
	v_fma_f32 v41, -v29, v37, 1.0
	v_div_scale_f32 v30, vcc, v27, v1, v27
	v_fma_f32 v43, -v31, v38, 1.0
	v_fmac_f32_e32 v37, v41, v37
	v_div_scale_f32 v32, s[4:5], v26, v0, v26
	v_fma_f32 v48, -v33, v39, 1.0
	v_fmac_f32_e32 v38, v43, v38
	v_mul_f32_e32 v41, v30, v37
	v_div_scale_f32 v34, s[6:7], v5, v3, v5
	v_fmac_f32_e32 v39, v48, v39
	v_mul_f32_e32 v43, v32, v38
	v_fma_f32 v51, -v29, v41, v30
	v_mul_f32_e32 v48, v34, v39
	v_fma_f32 v56, -v31, v43, v32
	v_fmac_f32_e32 v41, v51, v37
	v_fma_f32 v57, -v33, v48, v34
	v_fmac_f32_e32 v43, v56, v38
	v_fma_f32 v29, -v29, v41, v30
	v_fmac_f32_e32 v48, v57, v39
	v_fma_f32 v30, -v31, v43, v32
	v_div_fmas_f32 v29, v29, v37, v41
	s_mov_b64 vcc, s[4:5]
	v_fma_f32 v31, -v33, v48, v34
	v_div_fixup_f32 v1, v29, v1, v27
	v_div_fmas_f32 v27, v30, v38, v43
	s_mov_b64 vcc, s[6:7]
	v_div_fmas_f32 v29, v31, v39, v48
	s_nop 0
	v_pk_mul_f32 v[30:31], v[188:189], v[64:65]
	v_div_scale_f32 v35, s[8:9], v2, v2, v4
	v_pk_fma_f32 v[30:31], v[180:181], v[58:59], v[30:31]
	v_div_fixup_f32 v3, v29, v3, v5
	s_nop 0
	v_pk_fma_f32 v[8:9], v[196:197], v[66:67], v[30:31]
	v_rcp_f32_e32 v40, v35
	v_mul_f32_e32 v5, 0xbfb8aa3b, v8
	v_exp_f32_e32 v30, v5
	v_mul_f32_e32 v5, 0xbfb8aa3b, v9
	v_exp_f32_e32 v31, v5
	v_fma_f32 v49, -v35, v40, 1.0
	v_div_scale_f32 v36, s[8:9], v4, v2, v4
	v_fmac_f32_e32 v40, v49, v40
	v_pk_add_f32 v[30:31], v[30:31], 1.0 op_sel_hi:[1,0]
	v_mul_f32_e32 v49, v36, v40
	v_div_scale_f32 v29, s[4:5], v31, v31, v9
	v_fma_f32 v5, -v35, v49, v36
	v_rcp_f32_e32 v34, v29
	v_fmac_f32_e32 v49, v5, v40
	v_fma_f32 v5, -v35, v49, v36
	s_mov_b64 vcc, s[8:9]
	v_div_fmas_f32 v5, v5, v40, v49
	v_div_fixup_f32 v2, v5, v2, v4
	v_fma_f32 v4, -v29, v34, 1.0
	v_fmac_f32_e32 v34, v4, v34
	v_div_scale_f32 v4, vcc, v9, v31, v9
	v_mul_f32_e32 v5, v4, v34
	v_fma_f32 v35, -v29, v5, v4
	v_fmac_f32_e32 v5, v35, v34
	v_mul_f32_e32 v36, v198, v25
	v_mov_b32_e32 v10, v183
	v_fma_f32 v4, -v29, v5, v4
	v_mov_b32_e32 v11, v199
	v_pk_mul_f32 v[10:11], v[10:11], v[60:61]
	v_div_scale_f32 v29, s[4:5], v30, v30, v8
	v_div_fmas_f32 v4, v4, v34, v5
	v_mul_f32_e32 v34, v182, v23
	v_mov_b32_e32 v35, v10
	v_rcp_f32_e32 v38, v29
	v_pk_fma_f32 v[6:7], v[190:191], v[6:7], v[34:35]
	v_mov_b32_e32 v37, v11
	v_pk_add_f32 v[6:7], v[6:7], v[36:37]
	v_div_fixup_f32 v5, v4, v31, v9
	v_mul_f32_e32 v10, 0xbfb8aa3b, v6
	v_mul_f32_e32 v11, 0xbfb8aa3b, v7
	v_exp_f32_e32 v10, v10
	v_exp_f32_e32 v11, v11
	v_fma_f32 v4, -v29, v38, 1.0
	v_fmac_f32_e32 v38, v4, v38
	v_div_scale_f32 v4, vcc, v8, v30, v8
	v_mul_f32_e32 v9, v4, v38
	v_fma_f32 v23, -v29, v9, v4
	v_pk_add_f32 v[10:11], v[10:11], 1.0 op_sel_hi:[1,0]
	v_fmac_f32_e32 v9, v23, v38
	v_div_scale_f32 v23, s[4:5], v11, v11, v7
	v_rcp_f32_e32 v25, v23
	v_fma_f32 v4, -v29, v9, v4
	v_div_fmas_f32 v4, v4, v38, v9
	v_div_fixup_f32 v4, v4, v30, v8
	v_fma_f32 v29, -v23, v25, 1.0
	v_fmac_f32_e32 v25, v29, v25
	v_div_scale_f32 v29, vcc, v7, v11, v7
	v_mul_f32_e32 v30, v29, v25
	v_fma_f32 v31, -v23, v30, v29
	v_fmac_f32_e32 v30, v31, v25
	v_fma_f32 v23, -v23, v30, v29
	v_div_scale_f32 v29, s[4:5], v10, v10, v6
	v_rcp_f32_e32 v31, v29
	v_div_fmas_f32 v23, v23, v25, v30
	v_div_fixup_f32 v7, v23, v11, v7
	v_div_fixup_f32 v0, v27, v0, v26
	v_fma_f32 v11, -v29, v31, 1.0
	v_fmac_f32_e32 v31, v11, v31
	v_div_scale_f32 v11, vcc, v6, v10, v6
	v_mul_f32_e32 v23, v11, v31
	v_fma_f32 v25, -v29, v23, v11
	v_fmac_f32_e32 v23, v25, v31
	v_pk_mul_f32 v[26:27], v[0:1], v[0:1]
	v_fma_f32 v11, -v29, v23, v11
	v_pk_mul_f32 v[32:33], v[2:3], v[2:3]
	v_div_fmas_f32 v11, v11, v31, v23
	v_add_f32_e32 v23, v26, v27
	v_add_f32_e32 v23, v23, v32
	v_pk_mul_f32 v[8:9], v[4:5], v[4:5]
	v_add_f32_e32 v23, v23, v33
	v_div_fixup_f32 v6, v11, v10, v6
	v_add_f32_e32 v8, v23, v8
	v_pk_mul_f32 v[10:11], v[6:7], v[6:7]
	v_add_f32_e32 v8, v8, v9
	v_add_f32_e32 v8, v8, v10
	v_add_f32_e32 v8, v8, v11
	v_cmp_gt_i32_e32 vcc, 64, v24
	s_nop 0
	v_add_f32_dpp v8, v8, v8 quad_perm:[1,0,3,2] row_mask:0xf bank_mask:0xf bound_ctrl:1
	s_nop 1
	v_add_f32_dpp v8, v8, v8 quad_perm:[2,3,0,1] row_mask:0xf bank_mask:0xf bound_ctrl:1
	s_nop 1
	v_mov_b32_dpp v9, v8 row_half_mirror row_mask:0xf bank_mask:0xf bound_ctrl:1
	s_and_saveexec_b64 s[6:7], vcc
	s_cbranch_execz .LBB0_479
	v_add_f32_e32 v8, v8, v9
	v_add_f32_e32 v8, 0x358637bd, v8
	v_mul_f32_e32 v9, 0x4b800000, v8
	v_cmp_gt_f32_e32 vcc, s28, v8
	v_cmp_gt_i32_e64 s[4:5], 32, v24
	s_nop 0
	v_cndmask_b32_e32 v8, v8, v9, vcc
	v_rsq_f32_e32 v8, v8
	v_cndmask_b32_e64 v9, 1.0, v28, s[4:5]
	v_mul_f32_e32 v10, 0x45800000, v8
	v_cndmask_b32_e32 v8, v8, v10, vcc
	v_mul_f32_e32 v8, v9, v8
	v_pk_mul_f32 v[6:7], v[6:7], v[8:9] op_sel_hi:[1,0]
	v_pk_mul_f32 v[4:5], v[4:5], v[8:9] op_sel_hi:[1,0]
	v_pk_mul_f32 v[2:3], v[2:3], v[8:9] op_sel_hi:[1,0]
	v_pk_mul_f32 v[0:1], v[0:1], v[8:9] op_sel_hi:[1,0]
	s_branch .LBB0_479

.Lxb_done_8:
.LBB0_2219:
	s_or_b64 exec, exec, s[4:5]
	v_mov_b32_e32 v50, v174
	s_mov_b64 s[68:69], s[84:85]
	s_load_dwordx2 s[14:15], s[90:91], 0x118
	s_waitcnt lgkmcnt(0)
	s_barrier
	s_mov_b32 s76, 0
	s_add_u32 s70, s68, 0x5d52000
	s_addc_u32 s71, s69, 0
	s_ashr_i32 s80, s76, 31
	s_add_u32 s2, s90, s76
	v_mov_b32_e32 v0, 0
	s_mov_b32 s77, s88
	s_mov_b32 s79, s86
	s_addc_u32 s3, s91, s80
	s_load_dwordx2 s[2:3], s[2:3], 0xa0
	v_mov_b32_e32 v25, 0
	v_lshlrev_b32_e32 v42, 3, v50
	s_waitcnt lgkmcnt(0)
	s_add_u32 s10, s2, 0x2400
	s_addc_u32 s11, s3, 0
	s_add_u32 s12, s68, 0xb932000
	s_addc_u32 s13, s69, 0
	s_add_i32 s2, s79, s77
	s_cmpk_gt_i32 s2, 0x8ff
	s_mov_b32 s3, s77
	s_cbranch_scc1 .LBB0_2234
	v_and_b32_e32 v26, 0xf8, v42
	s_lshl_b32 s20, s79, 1
	s_lshl_b32 s21, s2, 9
	s_lshl_b32 s22, s79, 10
	s_lshl_b32 s23, s2, 12
	s_lshl_b32 s24, s79, 13
	s_lshl_b32 s25, s77, 9
	s_lshl_b32 s26, s77, 12
	s_mov_b32 s27, 0x2aaaaaab
	s_mov_b32 s28, 0x5ffff
	v_mov_b32_e32 v27, 0xff
	v_mov_b32_e32 v35, 0x7ff
	s_movk_i32 s29, 0x1660
	v_mov_b64_e32 v[28:29], s[70:71]
	s_movk_i32 s30, 0xfd00
	s_mov_b64 s[16:17], 0x840
	s_movk_i32 s31, 0x1000
	s_movk_i32 s33, 0xffa0
	s_mov_b64 s[18:19], 0x1800
	s_mov_b32 s34, 0x800000
	s_mov_b32 s35, 0x600000
	v_mov_b32_e32 v43, 0x3e000000
	v_mov_b32_e32 v44, v42
	v_mov_b32_e32 v45, v50
	s_mov_b32 s3, s77
	s_waitcnt lgkmcnt(0)
	s_branch .LBB0_2222

.LBB0_2230:
	s_or_b64 exec, exec, s[4:5]
	v_lshl_add_u64 v[40:41], v[38:39], 2, s[10:11]
	s_waitcnt vmcnt(0) lgkmcnt(0)
	s_nop 0
	s_nop 0
	v_add_co_u32_e32 v38, vcc, s31, v40
	s_waitcnt lgkmcnt(0)
	v_lshlrev_b32_e32 v68, 16, v20
	v_addc_co_u32_e32 v39, vcc, 0, v41, vcc
	s_nop 0
	s_nop 0
	s_nop 0
	v_and_b32_e32 v69, 0xffff0000, v20
	v_lshlrev_b32_e32 v70, 16, v21
	v_and_b32_e32 v71, 0xffff0000, v21
	v_lshl_add_u64 v[20:21], v[40:41], 0, s[18:19]
	v_mad_u64_u32 v[38:39], s[4:5], v32, s33, v[24:25]
	v_lshlrev_b32_e32 v72, 16, v22
	v_and_b32_e32 v73, 0xffff0000, v22
	v_lshlrev_b32_e32 v24, 16, v23
	v_and_b32_e32 v74, 0xffff0000, v23
	s_nop 0
	v_lshlrev_b32_e32 v76, 16, v16
	v_and_b32_e32 v77, 0xffff0000, v16
	v_lshlrev_b32_e32 v16, 16, v17
	v_and_b32_e32 v17, 0xffff0000, v17
	v_lshlrev_b32_e32 v40, 16, v12
	v_and_b32_e32 v41, 0xffff0000, v12
	v_lshlrev_b32_e32 v12, 16, v13
	v_and_b32_e32 v13, 0xffff0000, v13
	v_and_b32_e32 v75, 0xffff0000, v15
	v_lshlrev_b32_e32 v80, 16, v14
	v_and_b32_e32 v81, 0xffff0000, v14
	v_lshlrev_b32_e32 v78, 16, v18
	v_and_b32_e32 v79, 0xffff0000, v18
	v_lshlrev_b32_e32 v18, 16, v19
	v_and_b32_e32 v19, 0xffff0000, v19
	v_pk_mul_f32 v[52:53], v[184:185], v[76:77]
	v_pk_mul_f32 v[16:17], v[186:187], v[16:17]
	v_pk_fma_f32 v[46:47], v[176:177], v[68:69], v[52:53]
	v_pk_fma_f32 v[16:17], v[178:179], v[70:71], v[16:17]
	s_nop 0
	v_pk_fma_f32 v[40:41], v[192:193], v[40:41], v[46:47]
	v_pk_fma_f32 v[16:17], v[194:195], v[12:13], v[16:17]
	v_mul_f32_e32 v12, 0xbfb8aa3b, v40
	v_mul_f32_e32 v13, 0xbfb8aa3b, v41
	v_exp_f32_e32 v12, v12
	v_exp_f32_e32 v13, v13
	v_mul_f32_e32 v31, 0xbfb8aa3b, v16
	v_mul_f32_e32 v33, 0xbfb8aa3b, v17
	v_exp_f32_e32 v46, v31
	v_exp_f32_e32 v47, v33
	v_pk_add_f32 v[12:13], v[12:13], 1.0 op_sel_hi:[1,0]
	v_lshlrev_b32_e32 v31, 16, v15
	v_div_scale_f32 v33, s[4:5], v13, v13, v41
	v_pk_add_f32 v[14:15], v[46:47], 1.0 op_sel_hi:[1,0]
	v_div_scale_f32 v46, s[4:5], v12, v12, v40
	v_rcp_f32_e32 v53, v33
	v_div_scale_f32 v48, s[6:7], v15, v15, v17
	v_rcp_f32_e32 v54, v46
	v_rcp_f32_e32 v55, v48
	v_fma_f32 v57, -v33, v53, 1.0
	v_div_scale_f32 v39, vcc, v41, v13, v41
	v_fma_f32 v58, -v46, v54, 1.0
	v_fmac_f32_e32 v53, v57, v53
	v_div_scale_f32 v47, s[4:5], v40, v12, v40
	v_fma_f32 v59, -v48, v55, 1.0
	v_fmac_f32_e32 v54, v58, v54
	v_mul_f32_e32 v57, v39, v53
	v_div_scale_f32 v49, s[6:7], v17, v15, v17
	v_fmac_f32_e32 v55, v59, v55
	v_mul_f32_e32 v58, v47, v54
	v_fma_f32 v69, -v33, v57, v39
	v_mul_f32_e32 v59, v49, v55
	v_fma_f32 v70, -v46, v58, v47
	v_fmac_f32_e32 v57, v69, v53
	v_fma_f32 v71, -v48, v59, v49
	v_fmac_f32_e32 v58, v70, v54
	v_fma_f32 v33, -v33, v57, v39
	v_fmac_f32_e32 v59, v71, v55
	v_fma_f32 v39, -v46, v58, v47
	v_div_fmas_f32 v33, v33, v53, v57
	s_mov_b64 vcc, s[4:5]
	v_fma_f32 v46, -v48, v59, v49
	v_div_fixup_f32 v13, v33, v13, v41
	v_div_fmas_f32 v33, v39, v54, v58
	s_mov_b64 vcc, s[6:7]
	v_div_fixup_f32 v12, v33, v12, v40
	v_div_fmas_f32 v33, v46, v55, v59
	s_nop 0
	v_pk_mul_f32 v[46:47], v[188:189], v[78:79]
	v_div_scale_f32 v51, s[8:9], v14, v14, v16
	v_pk_fma_f32 v[46:47], v[180:181], v[72:73], v[46:47]
	v_div_fixup_f32 v15, v33, v15, v17
	s_nop 0
	v_pk_fma_f32 v[20:21], v[196:197], v[80:81], v[46:47]
	v_rcp_f32_e32 v56, v51
	v_mul_f32_e32 v17, 0xbfb8aa3b, v20
	v_exp_f32_e32 v46, v17
	v_mul_f32_e32 v17, 0xbfb8aa3b, v21
	v_exp_f32_e32 v47, v17
	v_fma_f32 v68, -v51, v56, 1.0
	v_div_scale_f32 v52, s[8:9], v16, v14, v16
	v_fmac_f32_e32 v56, v68, v56
	v_pk_add_f32 v[46:47], v[46:47], 1.0 op_sel_hi:[1,0]
	v_mul_f32_e32 v68, v52, v56
	v_div_scale_f32 v33, s[4:5], v47, v47, v21
	v_fma_f32 v17, -v51, v68, v52
	v_rcp_f32_e32 v39, v33
	v_fmac_f32_e32 v68, v17, v56
	v_fma_f32 v17, -v51, v68, v52
	s_mov_b64 vcc, s[8:9]
	v_div_fmas_f32 v17, v17, v56, v68
	v_div_fixup_f32 v14, v17, v14, v16
	v_fma_f32 v16, -v33, v39, 1.0
	v_fmac_f32_e32 v39, v16, v39
	v_div_scale_f32 v16, vcc, v21, v47, v21
	v_mul_f32_e32 v17, v16, v39
	v_fma_f32 v51, -v33, v17, v16
	v_mul_f32_e32 v54, v198, v31
	v_mov_b32_e32 v22, v183
	v_fmac_f32_e32 v17, v51, v39
	v_mov_b32_e32 v23, v199
	v_pk_mul_f32 v[22:23], v[22:23], v[74:75]
	v_fma_f32 v16, -v33, v17, v16
	v_div_scale_f32 v33, s[4:5], v46, v46, v20
	v_mul_f32_e32 v52, v182, v24
	v_mov_b32_e32 v53, v22
	v_rcp_f32_e32 v51, v33
	v_pk_fma_f32 v[18:19], v[190:191], v[18:19], v[52:53]
	v_mov_b32_e32 v55, v23
	v_pk_add_f32 v[18:19], v[18:19], v[54:55]
	v_div_fmas_f32 v16, v16, v39, v17
	v_mul_f32_e32 v22, 0xbfb8aa3b, v18
	v_mul_f32_e32 v23, 0xbfb8aa3b, v19
	v_exp_f32_e32 v22, v22
	v_exp_f32_e32 v23, v23
	v_div_fixup_f32 v17, v16, v47, v21
	v_fma_f32 v16, -v33, v51, 1.0
	v_fmac_f32_e32 v51, v16, v51
	v_div_scale_f32 v16, vcc, v20, v46, v20
	v_mul_f32_e32 v21, v16, v51
	v_fma_f32 v24, -v33, v21, v16
	v_pk_add_f32 v[22:23], v[22:23], 1.0 op_sel_hi:[1,0]
	v_fmac_f32_e32 v21, v24, v51
	v_div_scale_f32 v24, s[4:5], v23, v23, v19
	v_rcp_f32_e32 v31, v24
	v_fma_f32 v16, -v33, v21, v16
	v_div_fmas_f32 v16, v16, v51, v21
	v_div_fixup_f32 v16, v16, v46, v20
	v_fma_f32 v33, -v24, v31, 1.0
	v_fmac_f32_e32 v31, v33, v31
	v_div_scale_f32 v33, vcc, v19, v23, v19
	v_mul_f32_e32 v39, v33, v31
	v_fma_f32 v46, -v24, v39, v33
	v_fmac_f32_e32 v39, v46, v31
	v_fma_f32 v24, -v24, v39, v33
	v_div_scale_f32 v33, s[4:5], v22, v22, v18
	v_rcp_f32_e32 v46, v33
	v_div_fmas_f32 v24, v24, v31, v39
	v_div_fixup_f32 v19, v24, v23, v19
	v_pk_mul_f32 v[40:41], v[12:13], v[12:13]
	v_fma_f32 v23, -v33, v46, 1.0
	v_fmac_f32_e32 v46, v23, v46
	v_div_scale_f32 v23, vcc, v18, v22, v18
	v_mul_f32_e32 v24, v23, v46
	v_fma_f32 v31, -v33, v24, v23
	v_fmac_f32_e32 v24, v31, v46
	v_fma_f32 v23, -v33, v24, v23
	v_pk_mul_f32 v[48:49], v[14:15], v[14:15]
	v_div_fmas_f32 v23, v23, v46, v24
	v_add_f32_e32 v24, v40, v41
	v_add_f32_e32 v24, v24, v48
	v_pk_mul_f32 v[20:21], v[16:17], v[16:17]
	v_add_f32_e32 v24, v24, v49
	v_div_fixup_f32 v18, v23, v22, v18
	v_add_f32_e32 v20, v24, v20
	v_pk_mul_f32 v[22:23], v[18:19], v[18:19]
	v_add_f32_e32 v20, v20, v21
	v_add_f32_e32 v20, v20, v22
	v_add_f32_e32 v20, v20, v23
	v_cmp_gt_i32_e32 vcc, 64, v38
	s_nop 0
	v_add_f32_dpp v20, v20, v20 quad_perm:[1,0,3,2] row_mask:0xf bank_mask:0xf bound_ctrl:1
	s_nop 1
	v_add_f32_dpp v20, v20, v20 quad_perm:[2,3,0,1] row_mask:0xf bank_mask:0xf bound_ctrl:1
	s_nop 1
	v_mov_b32_dpp v21, v20 row_half_mirror row_mask:0xf bank_mask:0xf bound_ctrl:1
	s_and_saveexec_b64 s[6:7], vcc
	s_cbranch_execz .LBB0_2232
	v_add_f32_e32 v20, v20, v21
	v_add_f32_e32 v20, 0x358637bd, v20
	v_mul_f32_e32 v21, 0x4b800000, v20
	v_cmp_gt_f32_e32 vcc, s34, v20
	v_cmp_gt_i32_e64 s[4:5], 32, v38
	s_nop 0
	v_cndmask_b32_e32 v20, v20, v21, vcc
	v_rsq_f32_e32 v20, v20
	v_cndmask_b32_e64 v21, 1.0, v43, s[4:5]
	v_mul_f32_e32 v22, 0x45800000, v20
	v_cndmask_b32_e32 v20, v20, v22, vcc
	v_mul_f32_e32 v20, v21, v20
	v_pk_mul_f32 v[18:19], v[18:19], v[20:21] op_sel_hi:[1,0]
	v_pk_mul_f32 v[16:17], v[16:17], v[20:21] op_sel_hi:[1,0]
	v_pk_mul_f32 v[14:15], v[14:15], v[20:21] op_sel_hi:[1,0]
	v_pk_mul_f32 v[12:13], v[12:13], v[20:21] op_sel_hi:[1,0]

.LBB0_2234:
	s_cmpk_gt_i32 s3, 0x8ff
	s_cbranch_scc1 .LBB0_2243
	v_and_b32_e32 v0, 0xf8, v42
	v_mov_b32_e32 v13, 0
	v_lshl_add_u32 v14, s3, 9, v50
	s_lshl_b32 s20, s79, 9
	v_lshl_add_u32 v16, s3, 12, v42
	s_lshl_b32 s21, s79, 12
	s_mov_b32 s22, 0x2aaaaaab
	s_mov_b32 s23, 0x5ffff
	v_mov_b32_e32 v15, 0xff
	v_mov_b32_e32 v17, 0x7ff
	s_movk_i32 s24, 0x1660
	v_mov_b64_e32 v[18:19], s[70:71]
	s_movk_i32 s25, 0xfd00
	s_mov_b64 s[16:17], 0x840
	s_movk_i32 s26, 0x1000
	s_movk_i32 s27, 0xffa0
	s_mov_b64 s[18:19], 0x1800
	s_mov_b32 s28, 0x800000
	s_mov_b32 s29, 0x600000
	v_mov_b64_e32 v[20:21], s[12:13]
	v_lshlrev_b32_e32 v12, 1, v0
	v_mov_b32_e32 v28, 0x3e000000
	s_waitcnt lgkmcnt(0)
	s_branch .LBB0_2237

.LBB0_2241:
	s_or_b64 exec, exec, s[4:5]
	v_lshl_add_u64 v[26:27], v[24:25], 2, s[10:11]
	s_waitcnt vmcnt(0) lgkmcnt(0)
	s_nop 0
	s_nop 0
	v_add_co_u32_e32 v24, vcc, s26, v26
	s_waitcnt lgkmcnt(0)
	v_lshlrev_b32_e32 v48, 16, v8
	v_addc_co_u32_e32 v25, vcc, 0, v27, vcc
	s_nop 0
	s_nop 0
	s_nop 0
	v_and_b32_e32 v49, 0xffff0000, v8
	v_lshlrev_b32_e32 v56, 16, v9
	v_and_b32_e32 v57, 0xffff0000, v9
	v_lshl_add_u64 v[8:9], v[26:27], 0, s[18:19]
	v_lshlrev_b32_e32 v58, 16, v10
	v_and_b32_e32 v59, 0xffff0000, v10
	v_lshlrev_b32_e32 v23, 16, v11
	v_and_b32_e32 v60, 0xffff0000, v11
	s_nop 0
	v_lshlrev_b32_e32 v62, 16, v4
	v_and_b32_e32 v63, 0xffff0000, v4
	v_lshlrev_b32_e32 v4, 16, v5
	v_and_b32_e32 v5, 0xffff0000, v5
	v_lshlrev_b32_e32 v26, 16, v0
	v_and_b32_e32 v27, 0xffff0000, v0
	v_lshlrev_b32_e32 v0, 16, v1
	v_and_b32_e32 v1, 0xffff0000, v1
	v_mad_u64_u32 v[24:25], s[4:5], v22, s27, v[14:15]
	v_and_b32_e32 v61, 0xffff0000, v3
	v_lshlrev_b32_e32 v66, 16, v2
	v_and_b32_e32 v67, 0xffff0000, v2
	v_lshlrev_b32_e32 v64, 16, v6
	v_and_b32_e32 v65, 0xffff0000, v6
	v_lshlrev_b32_e32 v6, 16, v7
	v_and_b32_e32 v7, 0xffff0000, v7
	v_pk_mul_f32 v[34:35], v[184:185], v[62:63]
	v_pk_mul_f32 v[4:5], v[186:187], v[4:5]
	v_pk_fma_f32 v[30:31], v[176:177], v[48:49], v[34:35]
	v_pk_fma_f32 v[4:5], v[178:179], v[56:57], v[4:5]
	s_nop 0
	v_pk_fma_f32 v[26:27], v[192:193], v[26:27], v[30:31]
	v_pk_fma_f32 v[4:5], v[194:195], v[0:1], v[4:5]
	v_mul_f32_e32 v0, 0xbfb8aa3b, v26
	v_mul_f32_e32 v1, 0xbfb8aa3b, v27
	v_exp_f32_e32 v0, v0
	v_exp_f32_e32 v1, v1
	v_mul_f32_e32 v25, 0xbfb8aa3b, v4
	v_mul_f32_e32 v29, 0xbfb8aa3b, v5
	v_exp_f32_e32 v30, v25
	v_exp_f32_e32 v31, v29
	v_pk_add_f32 v[0:1], v[0:1], 1.0 op_sel_hi:[1,0]
	v_lshlrev_b32_e32 v25, 16, v3
	v_div_scale_f32 v29, s[4:5], v1, v1, v27
	v_pk_add_f32 v[2:3], v[30:31], 1.0 op_sel_hi:[1,0]
	v_div_scale_f32 v31, s[4:5], v0, v0, v26
	v_rcp_f32_e32 v37, v29
	v_div_scale_f32 v33, s[6:7], v3, v3, v5
	v_rcp_f32_e32 v38, v31
	v_rcp_f32_e32 v39, v33
	v_fma_f32 v41, -v29, v37, 1.0
	v_div_scale_f32 v30, vcc, v27, v1, v27
	v_fma_f32 v43, -v31, v38, 1.0
	v_fmac_f32_e32 v37, v41, v37
	v_div_scale_f32 v32, s[4:5], v26, v0, v26
	v_fma_f32 v48, -v33, v39, 1.0
	v_fmac_f32_e32 v38, v43, v38
	v_mul_f32_e32 v41, v30, v37
	v_div_scale_f32 v34, s[6:7], v5, v3, v5
	v_fmac_f32_e32 v39, v48, v39
	v_mul_f32_e32 v43, v32, v38
	v_fma_f32 v51, -v29, v41, v30
	v_mul_f32_e32 v48, v34, v39
	v_fma_f32 v56, -v31, v43, v32
	v_fmac_f32_e32 v41, v51, v37
	v_fma_f32 v57, -v33, v48, v34
	v_fmac_f32_e32 v43, v56, v38
	v_fma_f32 v29, -v29, v41, v30
	v_fmac_f32_e32 v48, v57, v39
	v_fma_f32 v30, -v31, v43, v32
	v_div_fmas_f32 v29, v29, v37, v41
	s_mov_b64 vcc, s[4:5]
	v_fma_f32 v31, -v33, v48, v34
	v_div_fixup_f32 v1, v29, v1, v27
	v_div_fmas_f32 v27, v30, v38, v43
	s_mov_b64 vcc, s[6:7]
	v_div_fmas_f32 v29, v31, v39, v48
	s_nop 0
	v_pk_mul_f32 v[30:31], v[188:189], v[64:65]
	v_div_scale_f32 v35, s[8:9], v2, v2, v4
	v_pk_fma_f32 v[30:31], v[180:181], v[58:59], v[30:31]
	v_div_fixup_f32 v3, v29, v3, v5
	s_nop 0
	v_pk_fma_f32 v[8:9], v[196:197], v[66:67], v[30:31]
	v_rcp_f32_e32 v40, v35
	v_mul_f32_e32 v5, 0xbfb8aa3b, v8
	v_exp_f32_e32 v30, v5
	v_mul_f32_e32 v5, 0xbfb8aa3b, v9
	v_exp_f32_e32 v31, v5
	v_fma_f32 v49, -v35, v40, 1.0
	v_div_scale_f32 v36, s[8:9], v4, v2, v4
	v_fmac_f32_e32 v40, v49, v40
	v_pk_add_f32 v[30:31], v[30:31], 1.0 op_sel_hi:[1,0]
	v_mul_f32_e32 v49, v36, v40
	v_div_scale_f32 v29, s[4:5], v31, v31, v9
	v_fma_f32 v5, -v35, v49, v36
	v_rcp_f32_e32 v34, v29
	v_fmac_f32_e32 v49, v5, v40
	v_fma_f32 v5, -v35, v49, v36
	s_mov_b64 vcc, s[8:9]
	v_div_fmas_f32 v5, v5, v40, v49
	v_div_fixup_f32 v2, v5, v2, v4
	v_fma_f32 v4, -v29, v34, 1.0
	v_fmac_f32_e32 v34, v4, v34
	v_div_scale_f32 v4, vcc, v9, v31, v9
	v_mul_f32_e32 v5, v4, v34
	v_fma_f32 v35, -v29, v5, v4
	v_fmac_f32_e32 v5, v35, v34
	v_mul_f32_e32 v36, v198, v25
	v_mov_b32_e32 v10, v183
	v_fma_f32 v4, -v29, v5, v4
	v_mov_b32_e32 v11, v199
	v_pk_mul_f32 v[10:11], v[10:11], v[60:61]
	v_div_scale_f32 v29, s[4:5], v30, v30, v8
	v_div_fmas_f32 v4, v4, v34, v5
	v_mul_f32_e32 v34, v182, v23
	v_mov_b32_e32 v35, v10
	v_rcp_f32_e32 v38, v29
	v_pk_fma_f32 v[6:7], v[190:191], v[6:7], v[34:35]
	v_mov_b32_e32 v37, v11
	v_pk_add_f32 v[6:7], v[6:7], v[36:37]
	v_div_fixup_f32 v5, v4, v31, v9
	v_mul_f32_e32 v10, 0xbfb8aa3b, v6
	v_mul_f32_e32 v11, 0xbfb8aa3b, v7
	v_exp_f32_e32 v10, v10
	v_exp_f32_e32 v11, v11
	v_fma_f32 v4, -v29, v38, 1.0
	v_fmac_f32_e32 v38, v4, v38
	v_div_scale_f32 v4, vcc, v8, v30, v8
	v_mul_f32_e32 v9, v4, v38
	v_fma_f32 v23, -v29, v9, v4
	v_pk_add_f32 v[10:11], v[10:11], 1.0 op_sel_hi:[1,0]
	v_fmac_f32_e32 v9, v23, v38
	v_div_scale_f32 v23, s[4:5], v11, v11, v7
	v_rcp_f32_e32 v25, v23
	v_fma_f32 v4, -v29, v9, v4
	v_div_fmas_f32 v4, v4, v38, v9
	v_div_fixup_f32 v4, v4, v30, v8
	v_fma_f32 v29, -v23, v25, 1.0
	v_fmac_f32_e32 v25, v29, v25
	v_div_scale_f32 v29, vcc, v7, v11, v7
	v_mul_f32_e32 v30, v29, v25
	v_fma_f32 v31, -v23, v30, v29
	v_fmac_f32_e32 v30, v31, v25
	v_fma_f32 v23, -v23, v30, v29
	v_div_scale_f32 v29, s[4:5], v10, v10, v6
	v_rcp_f32_e32 v31, v29
	v_div_fmas_f32 v23, v23, v25, v30
	v_div_fixup_f32 v7, v23, v11, v7
	v_div_fixup_f32 v0, v27, v0, v26
	v_fma_f32 v11, -v29, v31, 1.0
	v_fmac_f32_e32 v31, v11, v31
	v_div_scale_f32 v11, vcc, v6, v10, v6
	v_mul_f32_e32 v23, v11, v31
	v_fma_f32 v25, -v29, v23, v11
	v_fmac_f32_e32 v23, v25, v31
	v_pk_mul_f32 v[26:27], v[0:1], v[0:1]
	v_fma_f32 v11, -v29, v23, v11
	v_pk_mul_f32 v[32:33], v[2:3], v[2:3]
	v_div_fmas_f32 v11, v11, v31, v23
	v_add_f32_e32 v23, v26, v27
	v_add_f32_e32 v23, v23, v32
	v_pk_mul_f32 v[8:9], v[4:5], v[4:5]
	v_add_f32_e32 v23, v23, v33
	v_div_fixup_f32 v6, v11, v10, v6
	v_add_f32_e32 v8, v23, v8
	v_pk_mul_f32 v[10:11], v[6:7], v[6:7]
	v_add_f32_e32 v8, v8, v9
	v_add_f32_e32 v8, v8, v10
	v_add_f32_e32 v8, v8, v11
	v_cmp_gt_i32_e32 vcc, 64, v24
	s_nop 0
	v_add_f32_dpp v8, v8, v8 quad_perm:[1,0,3,2] row_mask:0xf bank_mask:0xf bound_ctrl:1
	s_nop 1
	v_add_f32_dpp v8, v8, v8 quad_perm:[2,3,0,1] row_mask:0xf bank_mask:0xf bound_ctrl:1
	s_nop 1
	v_mov_b32_dpp v9, v8 row_half_mirror row_mask:0xf bank_mask:0xf bound_ctrl:1
	s_and_saveexec_b64 s[6:7], vcc
	s_cbranch_execz .LBB0_2236
	v_add_f32_e32 v8, v8, v9
	v_add_f32_e32 v8, 0x358637bd, v8
	v_mul_f32_e32 v9, 0x4b800000, v8
	v_cmp_gt_f32_e32 vcc, s28, v8
	v_cmp_gt_i32_e64 s[4:5], 32, v24
	s_nop 0
	v_cndmask_b32_e32 v8, v8, v9, vcc
	v_rsq_f32_e32 v8, v8
	v_cndmask_b32_e64 v9, 1.0, v28, s[4:5]
	v_mul_f32_e32 v10, 0x45800000, v8
	v_cndmask_b32_e32 v8, v8, v10, vcc
	v_mul_f32_e32 v8, v9, v8
	v_pk_mul_f32 v[6:7], v[6:7], v[8:9] op_sel_hi:[1,0]
	v_pk_mul_f32 v[4:5], v[4:5], v[8:9] op_sel_hi:[1,0]
	v_pk_mul_f32 v[2:3], v[2:3], v[8:9] op_sel_hi:[1,0]
	v_pk_mul_f32 v[0:1], v[0:1], v[8:9] op_sel_hi:[1,0]
	s_branch .LBB0_2236
